# v70 + the 12 LDS-DMA issues of the next K block interleaved two per gap behind the first six MFMAs (DMA issue in the MFMA shadow instead of ahead of the MFMA block)
# speedup vs baseline: 1.0070x; 1.0015x over previous
.Lgin_pollok:
	ds_read_b128 v[128:131], v144 offset:0
	ds_read_b128 v[148:151], v144 offset:4096
	ds_read_b128 v[164:167], v144 offset:8192
	ds_read_b128 v[180:183], v144 offset:12288
	ds_read_b128 v[132:135], v146 offset:0
	ds_read_b128 v[152:155], v146 offset:4096
	ds_read_b128 v[168:171], v146 offset:8192
	ds_read_b128 v[184:187], v146 offset:12288
	ds_read_b128 v[136:139], v147 offset:0
	ds_read_b128 v[156:159], v147 offset:4096
	ds_read_b128 v[172:175], v147 offset:8192
	ds_read_b128 v[188:191], v147 offset:12288
	ds_read_b128 v[140:143], v210 offset:0
	ds_read_b128 v[160:163], v210 offset:4096
	ds_read_b128 v[176:179], v210 offset:8192
	ds_read_b128 v[212:215], v210 offset:12288
	ds_read_b128 v[216:219], v211 offset:32768
	ds_read_b128 v[232:235], v211 offset:36864
	ds_read_b128 v[220:223], v248 offset:32768
	ds_read_b128 v[236:239], v248 offset:36864
	ds_read_b128 v[224:227], v249 offset:32768
	ds_read_b128 v[240:243], v249 offset:36864
	ds_read_b128 v[228:231], v250 offset:32768
	ds_read_b128 v[244:247], v250 offset:36864
	s_waitcnt lgkmcnt(0)
	s_barrier
	s_cmp_eq_u32 s16, 1
	s_cbranch_scc1 .Lgin_nodma
	ds_write2_b32 v145, v145, v145 offset1:16
	s_mov_b32 exec_hi, 0
	ds_write_b32 v145, v145 offset:32768
	ds_write_b32 v145, v145 offset:32832
	s_mov_b32 exec_hi, -1
	s_waitcnt lgkmcnt(0)
	s_mov_b32 m0, s22
	s_nop 0
	s_setprio 0
	v_mfma_f32_32x32x16_bf16 v[0:15], v[216:219], v[128:131], v[0:15]
	global_load_lds_dwordx4 v251, s[20:21]
	s_add_u32 m0, m0, 0x1000
	s_add_u32 s20, s20, 0x10000
	s_addc_u32 s21, s21, 0
	global_load_lds_dwordx4 v251, s[20:21]
	s_add_u32 m0, m0, 0x1000
	s_add_u32 s20, s20, 0x10000
	s_addc_u32 s21, s21, 0
	v_mfma_f32_32x32x16_bf16 v[16:31], v[232:235], v[128:131], v[16:31]
	global_load_lds_dwordx4 v251, s[20:21]
	s_add_u32 m0, m0, 0x1000
	s_add_u32 s20, s20, 0x10000
	s_addc_u32 s21, s21, 0
	global_load_lds_dwordx4 v251, s[20:21]
	s_add_u32 m0, m0, 0x1000
	s_add_u32 s20, s20, 0x10000
	s_addc_u32 s21, s21, 0
	v_mfma_f32_32x32x16_bf16 v[32:47], v[216:219], v[148:151], v[32:47]
	global_load_lds_dwordx4 v251, s[20:21]
	s_add_u32 m0, m0, 0x1000
	s_add_u32 s20, s20, 0x10000
	s_addc_u32 s21, s21, 0
	global_load_lds_dwordx4 v251, s[20:21]
	s_add_u32 m0, m0, 0x1000
	s_add_u32 s20, s20, 0x10000
	s_addc_u32 s21, s21, 0
	v_mfma_f32_32x32x16_bf16 v[48:63], v[232:235], v[148:151], v[48:63]
	global_load_lds_dwordx4 v251, s[20:21]
	s_add_u32 m0, m0, 0x1000
	s_add_u32 s20, s20, 0x10000
	s_addc_u32 s21, s21, 0
	global_load_lds_dwordx4 v251, s[20:21]
	s_add_u32 m0, m0, 0x1000
	s_sub_u32 s20, s20, 458624
	s_subb_u32 s21, s21, 0
	v_mfma_f32_32x32x16_bf16 v[64:79], v[216:219], v[164:167], v[64:79]
	global_load_lds_dwordx4 v251, s[24:25]
	s_add_u32 m0, m0, 0x1000
	s_add_u32 s24, s24, 0x10000
	s_addc_u32 s25, s25, 0
	global_load_lds_dwordx4 v251, s[24:25]
	s_add_u32 m0, m0, 0x1000
	s_add_u32 s24, s24, 0x10000
	s_addc_u32 s25, s25, 0
	v_mfma_f32_32x32x16_bf16 v[80:95], v[232:235], v[164:167], v[80:95]
	global_load_lds_dwordx4 v251, s[24:25]
	s_add_u32 m0, m0, 0x1000
	s_add_u32 s24, s24, 0x10000
	s_addc_u32 s25, s25, 0
	global_load_lds_dwordx4 v251, s[24:25]
	s_sub_u32 s24, s24, 196480
	s_subb_u32 s25, s25, 0
	v_mfma_f32_32x32x16_bf16 v[96:111], v[216:219], v[180:183], v[96:111]
	v_mfma_f32_32x32x16_bf16 v[112:127], v[232:235], v[180:183], v[112:127]
	v_mfma_f32_32x32x16_bf16 v[0:15], v[220:223], v[132:135], v[0:15]
	v_mfma_f32_32x32x16_bf16 v[16:31], v[236:239], v[132:135], v[16:31]
	v_mfma_f32_32x32x16_bf16 v[32:47], v[220:223], v[152:155], v[32:47]
	v_mfma_f32_32x32x16_bf16 v[48:63], v[236:239], v[152:155], v[48:63]
	v_mfma_f32_32x32x16_bf16 v[64:79], v[220:223], v[168:171], v[64:79]
	v_mfma_f32_32x32x16_bf16 v[80:95], v[236:239], v[168:171], v[80:95]
	v_mfma_f32_32x32x16_bf16 v[96:111], v[220:223], v[184:187], v[96:111]
	v_mfma_f32_32x32x16_bf16 v[112:127], v[236:239], v[184:187], v[112:127]
	v_mfma_f32_32x32x16_bf16 v[0:15], v[224:227], v[136:139], v[0:15]
	v_mfma_f32_32x32x16_bf16 v[16:31], v[240:243], v[136:139], v[16:31]
	v_mfma_f32_32x32x16_bf16 v[32:47], v[224:227], v[156:159], v[32:47]
	v_mfma_f32_32x32x16_bf16 v[48:63], v[240:243], v[156:159], v[48:63]
	v_and_b32_e32 v128, 63, v193
	v_and_b32_e32 v129, 15, v193
	v_lshlrev_b32_e32 v128, 7, v128
	v_lshl_add_u32 v128, v129, 2, v128
	v_add_u32_e32 v129, 8192, v128
	v_add_u32_e32 v130, 16384, v128
	v_add_u32_e32 v131, 24576, v128
	v_add_u32_e32 v132, 32768, v128
	v_add_u32_e32 v133, 40960, v128
	v_mfma_f32_32x32x16_bf16 v[64:79], v[224:227], v[172:175], v[64:79]
	v_mfma_f32_32x32x16_bf16 v[80:95], v[240:243], v[172:175], v[80:95]
	v_mfma_f32_32x32x16_bf16 v[96:111], v[224:227], v[188:191], v[96:111]
	v_mfma_f32_32x32x16_bf16 v[112:127], v[240:243], v[188:191], v[112:127]
	v_mfma_f32_32x32x16_bf16 v[0:15], v[228:231], v[140:143], v[0:15]
	v_mfma_f32_32x32x16_bf16 v[16:31], v[244:247], v[140:143], v[16:31]
	v_mfma_f32_32x32x16_bf16 v[32:47], v[228:231], v[160:163], v[32:47]
	v_mfma_f32_32x32x16_bf16 v[48:63], v[244:247], v[160:163], v[48:63]
	v_mfma_f32_32x32x16_bf16 v[64:79], v[228:231], v[176:179], v[64:79]
	v_mfma_f32_32x32x16_bf16 v[80:95], v[244:247], v[176:179], v[80:95]
	v_mfma_f32_32x32x16_bf16 v[96:111], v[228:231], v[212:215], v[96:111]
	v_mfma_f32_32x32x16_bf16 v[112:127], v[244:247], v[212:215], v[112:127]
	s_branch .Lgin_ktail

.Lgin_ktail:
	s_sub_u32 s16, s16, 1
	s_cmp_lg_u32 s16, 0
	s_cbranch_scc1 .Lgin_k
	s_nop 15
	s_nop 3
	v_and_b32_e32 v215, 31, v193
	v_mul_u32_u24_e32 v212, 0x110, v215
	v_bfe_u32 v215, v193, 5, 1
	v_lshl_add_u32 v212, v215, 3, v212
	v_bfe_u32 v215, v193, 7, 1
	v_mov_b32_e32 v216, 34816
	v_mad_u32_u24 v212, v215, v216, v212
	v_bfe_u32 v215, v193, 6, 1
	v_lshl_add_u32 v212, v215, 7, v212
	v_cvt_pk_bf16_f32 v128, v0, v1
	v_cvt_pk_bf16_f32 v129, v2, v3
	ds_write_b64 v212, v[128:129] offset:0
	v_cvt_pk_bf16_f32 v130, v4, v5
	v_cvt_pk_bf16_f32 v131, v6, v7
	ds_write_b64 v212, v[130:131] offset:16
	v_cvt_pk_bf16_f32 v132, v8, v9
	v_cvt_pk_bf16_f32 v133, v10, v11
	ds_write_b64 v212, v[132:133] offset:32
	v_cvt_pk_bf16_f32 v134, v12, v13
	v_cvt_pk_bf16_f32 v135, v14, v15
	ds_write_b64 v212, v[134:135] offset:48
	v_cvt_pk_bf16_f32 v136, v16, v17
	v_cvt_pk_bf16_f32 v137, v18, v19
	ds_write_b64 v212, v[136:137] offset:64
	v_cvt_pk_bf16_f32 v138, v20, v21
	v_cvt_pk_bf16_f32 v139, v22, v23
	ds_write_b64 v212, v[138:139] offset:80
	v_cvt_pk_bf16_f32 v140, v24, v25
	v_cvt_pk_bf16_f32 v141, v26, v27
	ds_write_b64 v212, v[140:141] offset:96
	v_cvt_pk_bf16_f32 v142, v28, v29
	v_cvt_pk_bf16_f32 v143, v30, v31
	ds_write_b64 v212, v[142:143] offset:112
	v_cvt_pk_bf16_f32 v128, v32, v33
	v_cvt_pk_bf16_f32 v129, v34, v35
	ds_write_b64 v212, v[128:129] offset:8704
	v_cvt_pk_bf16_f32 v130, v36, v37
	v_cvt_pk_bf16_f32 v131, v38, v39
	ds_write_b64 v212, v[130:131] offset:8720
	v_cvt_pk_bf16_f32 v132, v40, v41
	v_cvt_pk_bf16_f32 v133, v42, v43
	ds_write_b64 v212, v[132:133] offset:8736
	v_cvt_pk_bf16_f32 v134, v44, v45
	v_cvt_pk_bf16_f32 v135, v46, v47
	ds_write_b64 v212, v[134:135] offset:8752
	v_cvt_pk_bf16_f32 v136, v48, v49
	v_cvt_pk_bf16_f32 v137, v50, v51
	ds_write_b64 v212, v[136:137] offset:8768
	v_cvt_pk_bf16_f32 v138, v52, v53
	v_cvt_pk_bf16_f32 v139, v54, v55
	ds_write_b64 v212, v[138:139] offset:8784
	v_cvt_pk_bf16_f32 v140, v56, v57
	v_cvt_pk_bf16_f32 v141, v58, v59
	ds_write_b64 v212, v[140:141] offset:8800
	v_cvt_pk_bf16_f32 v142, v60, v61
	v_cvt_pk_bf16_f32 v143, v62, v63
	ds_write_b64 v212, v[142:143] offset:8816
	v_cvt_pk_bf16_f32 v128, v64, v65
	v_cvt_pk_bf16_f32 v129, v66, v67
	ds_write_b64 v212, v[128:129] offset:17408
	v_cvt_pk_bf16_f32 v130, v68, v69
	v_cvt_pk_bf16_f32 v131, v70, v71
	ds_write_b64 v212, v[130:131] offset:17424
	v_cvt_pk_bf16_f32 v132, v72, v73
	v_cvt_pk_bf16_f32 v133, v74, v75
	ds_write_b64 v212, v[132:133] offset:17440
	v_cvt_pk_bf16_f32 v134, v76, v77
	v_cvt_pk_bf16_f32 v135, v78, v79
	ds_write_b64 v212, v[134:135] offset:17456
	v_cvt_pk_bf16_f32 v136, v80, v81
	v_cvt_pk_bf16_f32 v137, v82, v83
	ds_write_b64 v212, v[136:137] offset:17472
	v_cvt_pk_bf16_f32 v138, v84, v85
	v_cvt_pk_bf16_f32 v139, v86, v87
	ds_write_b64 v212, v[138:139] offset:17488
	v_cvt_pk_bf16_f32 v140, v88, v89
	v_cvt_pk_bf16_f32 v141, v90, v91
	ds_write_b64 v212, v[140:141] offset:17504
	v_cvt_pk_bf16_f32 v142, v92, v93
	v_cvt_pk_bf16_f32 v143, v94, v95
	ds_write_b64 v212, v[142:143] offset:17520
	v_cvt_pk_bf16_f32 v128, v96, v97
	v_cvt_pk_bf16_f32 v129, v98, v99
	ds_write_b64 v212, v[128:129] offset:26112
	v_cvt_pk_bf16_f32 v130, v100, v101
	v_cvt_pk_bf16_f32 v131, v102, v103
	ds_write_b64 v212, v[130:131] offset:26128
	v_cvt_pk_bf16_f32 v132, v104, v105
	v_cvt_pk_bf16_f32 v133, v106, v107
	ds_write_b64 v212, v[132:133] offset:26144
	v_cvt_pk_bf16_f32 v134, v108, v109
	v_cvt_pk_bf16_f32 v135, v110, v111
	ds_write_b64 v212, v[134:135] offset:26160
	v_cvt_pk_bf16_f32 v136, v112, v113
	v_cvt_pk_bf16_f32 v137, v114, v115
	ds_write_b64 v212, v[136:137] offset:26176
	v_cvt_pk_bf16_f32 v138, v116, v117
	v_cvt_pk_bf16_f32 v139, v118, v119
	ds_write_b64 v212, v[138:139] offset:26192
	v_cvt_pk_bf16_f32 v140, v120, v121
	v_cvt_pk_bf16_f32 v141, v122, v123
	ds_write_b64 v212, v[140:141] offset:26208
	v_cvt_pk_bf16_f32 v142, v124, v125
	v_cvt_pk_bf16_f32 v143, v126, v127
	ds_write_b64 v212, v[142:143] offset:26224
	s_waitcnt lgkmcnt(0)
	s_barrier
	v_lshrrev_b32_e32 v215, 4, v193
	v_and_b32_e32 v216, 15, v193
	v_mul_u32_u24_e32 v213, 0x110, v215
	v_lshl_add_u32 v213, v216, 4, v213
	v_mul_lo_u32 v214, v215, s12
	v_lshl_add_u32 v214, v216, 4, v214
	s_lshl_b32 s28, s12, 4
	ds_read_b128 v[148:151], v213 offset:0
	ds_read_b128 v[152:155], v213 offset:4352
	ds_read_b128 v[156:159], v213 offset:8704
	ds_read_b128 v[160:163], v213 offset:13056
	ds_read_b128 v[164:167], v213 offset:17408
	ds_read_b128 v[168:171], v213 offset:21760
	ds_read_b128 v[172:175], v213 offset:26112
	ds_read_b128 v[176:179], v213 offset:30464
	ds_read_b128 v[180:183], v213 offset:34816
	ds_read_b128 v[184:187], v213 offset:39168
	ds_read_b128 v[188:191], v213 offset:43520
	ds_read_b128 v[220:223], v213 offset:47872
	ds_read_b128 v[224:227], v213 offset:52224
	ds_read_b128 v[228:231], v213 offset:56576
	ds_read_b128 v[232:235], v213 offset:60928
	ds_read_b128 v[236:239], v213 offset:65280
	s_waitcnt lgkmcnt(15)
	global_store_dwordx4 v214, v[148:151], s[26:27]
	s_add_u32 s26, s26, s28
	s_addc_u32 s27, s27, 0
	s_waitcnt lgkmcnt(14)
	global_store_dwordx4 v214, v[152:155], s[26:27]
	s_add_u32 s26, s26, s28
	s_addc_u32 s27, s27, 0
	s_waitcnt lgkmcnt(13)
	global_store_dwordx4 v214, v[156:159], s[26:27]
	s_add_u32 s26, s26, s28
	s_addc_u32 s27, s27, 0
	s_waitcnt lgkmcnt(12)
	global_store_dwordx4 v214, v[160:163], s[26:27]
	s_add_u32 s26, s26, s28
	s_addc_u32 s27, s27, 0
	s_waitcnt lgkmcnt(11)
	global_store_dwordx4 v214, v[164:167], s[26:27]
	s_add_u32 s26, s26, s28
	s_addc_u32 s27, s27, 0
	s_waitcnt lgkmcnt(10)
	global_store_dwordx4 v214, v[168:171], s[26:27]
	s_add_u32 s26, s26, s28
	s_addc_u32 s27, s27, 0
	s_waitcnt lgkmcnt(9)
	global_store_dwordx4 v214, v[172:175], s[26:27]
	s_add_u32 s26, s26, s28
	s_addc_u32 s27, s27, 0
	s_waitcnt lgkmcnt(8)
	global_store_dwordx4 v214, v[176:179], s[26:27]
	s_add_u32 s26, s26, s28
	s_addc_u32 s27, s27, 0
	s_waitcnt lgkmcnt(7)
	global_store_dwordx4 v214, v[180:183], s[26:27]
	s_add_u32 s26, s26, s28
	s_addc_u32 s27, s27, 0
	s_waitcnt lgkmcnt(6)
	global_store_dwordx4 v214, v[184:187], s[26:27]
	s_add_u32 s26, s26, s28
	s_addc_u32 s27, s27, 0
	s_waitcnt lgkmcnt(5)
	global_store_dwordx4 v214, v[188:191], s[26:27]
	s_add_u32 s26, s26, s28
	s_addc_u32 s27, s27, 0
	s_waitcnt lgkmcnt(4)
	global_store_dwordx4 v214, v[220:223], s[26:27]
	s_add_u32 s26, s26, s28
	s_addc_u32 s27, s27, 0
	s_waitcnt lgkmcnt(3)
	global_store_dwordx4 v214, v[224:227], s[26:27]
	s_add_u32 s26, s26, s28
	s_addc_u32 s27, s27, 0
	s_waitcnt lgkmcnt(2)
	global_store_dwordx4 v214, v[228:231], s[26:27]
	s_add_u32 s26, s26, s28
	s_addc_u32 s27, s27, 0
	s_waitcnt lgkmcnt(1)
	global_store_dwordx4 v214, v[232:235], s[26:27]
	s_add_u32 s26, s26, s28
	s_addc_u32 s27, s27, 0
	s_waitcnt lgkmcnt(0)
	global_store_dwordx4 v214, v[236:239], s[26:27]
	s_barrier
	s_add_u32 s0, s0, s6
	s_cmp_lt_u32 s0, s1
	s_cbranch_scc1 .Lgin_tile
	v_mov_b32_e32 v145, 0
